# merge: prefetch loads in MFMA gaps and sigmoid spread over the P-GEMM clusters (without the default-address move)
# speedup vs baseline: 1.0404x; 1.0070x over previous
; template <int BN>
; DI void gemm_main(f32x16 (&acc)[2][BN / 64], const GDesc& cur, const GDesc& nxt, GRegs<BN>& R, bool preloaded, char* smem) {
;     ...
;   for (int k0 = 0; k0 < K; k0 += 128) {
;     __syncthreads();
;     GM_STORE(R.ra0, R.rb0)
;     __syncthreads();
;     if (k0 + 128 < K) GM_LOAD(R.ra0, R.rb0, ap, wp, lda, ldw, k0 + 128)
;     else if (nxt.valid) GM_LOAD(R.ra0, R.rb0, apn, wpn, nxt.lda, nxt.ldw, 0)
;     GM_COMPUTE()
;     __syncthreads();
;     GM_STORE(R.ra1, R.rb1)
;     __syncthreads();
;     if (k0 + 192 < K) GM_LOAD(R.ra1, R.rb1, ap, wp, lda, ldw, k0 + 192)
;     else if (nxt.valid) GM_LOAD(R.ra1, R.rb1, apn, wpn, nxt.lda, nxt.ldw, 64)
;     GM_COMPUTE()
.LBB0_96:
	s_addk_i32 s4, 0x80
	s_setprio 1
	ds_read_b128 v[120:123], v117 offset:4608
	ds_read_b128 v[156:159], v117
	ds_read_b128 v[160:163], v117 offset:32
	ds_read_b128 v[164:167], v118 offset:18432
	ds_read_b128 v[174:177], v118 offset:18464
	s_waitcnt lgkmcnt(1)
	v_mfma_f32_32x32x16_bf16 v[48:63], v[156:159], v[164:167], v[48:63]
	ds_read_b128 v[156:159], v117 offset:4672
	global_load_dwordx4 v[72:75], v[64:65], off
	v_lshl_add_u64 v[28:29], v[28:29], 0, s[88:89]
	v_mfma_f32_32x32x16_bf16 v[32:47], v[120:123], v[164:167], v[32:47]
	ds_read_b128 v[120:123], v117 offset:4640
	global_load_dwordx4 v[80:83], v[78:79], off
	v_lshl_add_u64 v[30:31], v[30:31], 0, s[88:89]
	s_waitcnt lgkmcnt(2)
	v_mfma_f32_32x32x16_bf16 v[48:63], v[160:163], v[174:177], v[48:63]
	ds_read_b128 v[160:163], v118 offset:18496
	global_load_dwordx4 v[64:67], v[66:67], off
	v_lshl_add_u64 v[112:113], v[112:113], 0, s[88:89]
	s_waitcnt lgkmcnt(1)
	v_mfma_f32_32x32x16_bf16 v[32:47], v[120:123], v[174:177], v[32:47]
	ds_read_b128 v[120:123], v117 offset:64
	global_load_dwordx4 v[68:71], v[68:69], off
	s_waitcnt lgkmcnt(0)
	v_mfma_f32_32x32x16_bf16 v[48:63], v[120:123], v[160:163], v[48:63]
	global_load_dwordx4 v[76:79], v[76:77], off
	v_mfma_f32_32x32x16_bf16 v[32:47], v[156:159], v[160:163], v[32:47]
	ds_read_b128 v[160:163], v118 offset:18528
	ds_read_b128 v[156:159], v117 offset:4704
	global_load_dwordx4 v[84:87], v[84:85], off
	s_waitcnt lgkmcnt(0)
	v_mfma_f32_32x32x16_bf16 v[32:47], v[156:159], v[160:163], v[32:47]
	ds_read_b128 v[120:123], v117 offset:96
	v_lshl_add_u64 v[24:25], v[24:25], 0, s[88:89]
	s_waitcnt lgkmcnt(0)
	v_mfma_f32_32x32x16_bf16 v[48:63], v[120:123], v[160:163], v[48:63]
	v_lshl_add_u64 v[26:27], v[26:27], 0, s[88:89]
	s_setprio 0
	s_andn2_b64 vcc, exec, s[22:23]
	s_cbranch_vccz .LBB0_101

; DI float sigmoidf_(float x) { return 1.f / (1.f + __expf(-x)); }
; template <int BN>
; DI void gemm_main(f32x16 (&acc)[2][BN / 64], const GDesc& cur, const GDesc& nxt, GRegs<BN>& R, bool preloaded, char* smem) {
;     ...
;   for (int k0 = 0; k0 < K; k0 += 128) {
;     __syncthreads();
;     GM_STORE(R.ra0, R.rb0)
;     __syncthreads();
;     if (k0 + 128 < K) GM_LOAD(R.ra0, R.rb0, ap, wp, lda, ldw, k0 + 128)
;     else if (nxt.valid) GM_LOAD(R.ra0, R.rb0, apn, wpn, nxt.lda, nxt.ldw, 0)
;     GM_COMPUTE()
;     __syncthreads();
;     GM_STORE(R.ra1, R.rb1)
;     __syncthreads();
;     if (k0 + 192 < K) GM_LOAD(R.ra1, R.rb1, ap, wp, lda, ldw, k0 + 192)
;     else if (nxt.valid) GM_LOAD(R.ra1, R.rb1, apn, wpn, nxt.lda, nxt.ldw, 64)
;     GM_COMPUTE()
; DI void phase_merge(const Params& P, int layer, char* smem) {
;     ...
;       gemm_main<64>(G, dG, dP, R, k > 0, smem);
; #pragma unroll
;       for (int mi = 0; mi < 2; ++mi)
; #pragma unroll
;         for (int i = 0; i < 16; ++i) G[mi][0][i] = sigmoidf_(G[mi][0][i]);
.LBB0_99:
	s_setprio 1
	ds_read_b128 v[120:123], v117 offset:4608
	ds_read_b128 v[156:159], v117
	ds_read_b128 v[160:163], v117 offset:32
	ds_read_b128 v[164:167], v118 offset:18432
	ds_read_b128 v[174:177], v118 offset:18464
	s_waitcnt lgkmcnt(1)
	v_mfma_f32_32x32x16_bf16 v[48:63], v[156:159], v[164:167], v[48:63]
	ds_read_b128 v[156:159], v117 offset:4672
	global_load_dwordx4 v[96:99], v[88:89], off
	v_mfma_f32_32x32x16_bf16 v[32:47], v[120:123], v[164:167], v[32:47]
	ds_read_b128 v[120:123], v117 offset:4640
	global_load_dwordx4 v[104:107], v[102:103], off
	s_waitcnt lgkmcnt(2)
	v_mfma_f32_32x32x16_bf16 v[48:63], v[160:163], v[174:177], v[48:63]
	ds_read_b128 v[160:163], v118 offset:18496
	global_load_dwordx4 v[88:91], v[90:91], off
	s_waitcnt lgkmcnt(1)
	v_mfma_f32_32x32x16_bf16 v[32:47], v[120:123], v[174:177], v[32:47]
	ds_read_b128 v[120:123], v117 offset:64
	global_load_dwordx4 v[92:95], v[92:93], off
	s_waitcnt lgkmcnt(0)
	v_mfma_f32_32x32x16_bf16 v[48:63], v[120:123], v[160:163], v[48:63]
	global_load_dwordx4 v[100:103], v[100:101], off
	v_mfma_f32_32x32x16_bf16 v[32:47], v[156:159], v[160:163], v[32:47]
	ds_read_b128 v[160:163], v118 offset:18528
	ds_read_b128 v[156:159], v117 offset:4704
	global_load_dwordx4 v[108:111], v[108:109], off
	s_waitcnt lgkmcnt(0)
	v_mfma_f32_32x32x16_bf16 v[32:47], v[156:159], v[160:163], v[32:47]
	ds_read_b128 v[120:123], v117 offset:96
	s_waitcnt lgkmcnt(0)
	v_mfma_f32_32x32x16_bf16 v[48:63], v[120:123], v[160:163], v[48:63]
	s_setprio 0
	s_barrier
	ds_write_b128 v116, v[76:79]
	ds_write_b128 v116, v[68:71] offset:9216
	ds_write_b128 v116, v[64:67] offset:13824
	s_waitcnt vmcnt(6)
	ds_write_b128 v116, v[84:87] offset:23040
	s_cmpk_gt_u32 s4, 0x33f
	v_mov_b64_e32 v[76:77], v[4:5]
	v_mov_b64_e32 v[78:79], v[16:17]
	v_mov_b64_e32 v[68:69], v[18:19]
	v_mov_b64_e32 v[66:67], v[20:21]
	v_mov_b64_e32 v[64:65], v[6:7]
	v_mov_b64_e32 v[84:85], v[22:23]
	ds_write_b128 v116, v[80:83] offset:4608
	ds_write_b128 v116, v[72:75] offset:18432
	s_waitcnt lgkmcnt(0)
	s_barrier
	s_cbranch_scc1 .LBB0_96
	s_mov_b64 s[30:31], 0x4110280
	v_lshl_add_u64 v[76:77], v[114:115], 0, s[30:31]
	s_mov_b64 s[30:31], 0x4140280
	v_lshl_add_u64 v[66:67], v[114:115], 0, s[30:31]
	s_mov_b64 s[30:31], 0x4130280
	v_lshl_add_u64 v[68:69], v[114:115], 0, s[30:31]
	s_mov_b64 s[30:31], 0x4120280
	v_lshl_add_u64 v[64:65], v[28:29], 0, v[168:169]
	v_lshl_add_u64 v[84:85], v[26:27], 0, v[168:169]
	v_lshl_add_u64 v[78:79], v[114:115], 0, s[30:31]
	s_mov_b64 s[30:31], s[34:35]
	s_branch .LBB0_96
.LBB0_101:
	v_mov_b32_e32 v6, v171
	s_mov_b32 s4, 0x18000
	v_ashrrev_i32_e32 v7, 3, v6
	v_add_u32_e32 v0, s25, v7
	v_ashrrev_i32_e32 v1, 31, v0
	v_lshlrev_b64 v[2:3], 10, v[0:1]
	v_lshlrev_b32_e32 v4, 4, v6
	v_lshl_add_u64 v[2:3], s[16:17], 0, v[2:3]
	v_and_b32_e32 v168, 0x70, v4
	v_lshl_add_u64 v[162:163], v[2:3], 0, v[168:169]
	v_add_co_u32_e32 v166, vcc, s4, v162
	v_add_u32_e32 v2, s26, v7
	s_nop 0
	v_addc_co_u32_e32 v167, vcc, 0, v163, vcc
	s_mov_b32 s4, 0x10000
	v_ashrrev_i32_e32 v3, 31, v2
	v_add_co_u32_e32 v174, vcc, s4, v162
	v_lshlrev_b64 v[4:5], 10, v[2:3]
	s_nop 0
	v_addc_co_u32_e32 v175, vcc, 0, v163, vcc
	s_mov_b32 s4, 0x8000
	v_lshl_add_u64 v[4:5], s[14:15], 0, v[4:5]
	v_add_co_u32_e32 v176, vcc, s4, v162
	v_lshl_add_u64 v[164:165], v[4:5], 0, v[168:169]
	s_nop 0
	v_addc_co_u32_e32 v177, vcc, 0, v163, vcc
	v_add_co_u32_e32 v178, vcc, s4, v164
	v_mad_u64_u32 v[156:157], s[14:15], v7, s53, v[168:169]
	s_nop 0
	v_addc_co_u32_e32 v179, vcc, 0, v165, vcc
	s_barrier
	s_waitcnt vmcnt(7)
	ds_write_b128 v156, v[100:103]
	ds_write_b128 v156, v[104:107] offset:4608
	ds_write_b128 v156, v[92:95] offset:9216
	ds_write_b128 v156, v[88:91] offset:13824
	ds_write_b128 v156, v[96:99] offset:18432
	s_waitcnt vmcnt(6)
	ds_write_b128 v156, v[108:111] offset:23040
	s_waitcnt lgkmcnt(0)
	s_barrier
	global_load_dwordx4 v[88:91], v[166:167], off offset:256
	global_load_dwordx4 v[92:95], v[174:175], off offset:256
	global_load_dwordx4 v[96:99], v[164:165], off offset:256
	global_load_dwordx4 v[100:103], v[162:163], off offset:256
	global_load_dwordx4 v[108:111], v[176:177], off offset:256
	global_load_dwordx4 v[104:107], v[178:179], off offset:256
	s_add_i32 s4, s28, 1
	s_lshl_b32 s14, s4, 21
	v_readlane_b32 s22, v251, 2
	s_and_b32 s14, s14, 0x600000
	v_readlane_b32 s15, v254, 28
	v_lshlrev_b64 v[0:1], 11, v[0:1]
	v_readlane_b32 s23, v251, 3
	s_add_u32 s16, s15, s14
	v_readlane_b32 s14, v254, 29
	v_lshl_add_u64 v[0:1], s[22:23], 0, v[0:1]
	s_addc_u32 s17, s14, 0
	v_lshl_add_u64 v[160:161], v[0:1], 0, v[168:169]
	v_lshlrev_b64 v[0:1], 11, v[2:3]
	v_lshl_add_u64 v[0:1], s[16:17], 0, v[0:1]
	v_and_b32_e32 v4, 31, v6
	v_lshl_add_u64 v[158:159], v[0:1], 0, v[168:169]
	v_lshrrev_b32_e32 v0, 1, v6
	v_and_or_b32 v1, v0, s54, v4
	s_cmp_lg_u32 s28, 3
	v_and_b32_e32 v168, 16, v0
	v_and_or_b32 v181, v0, 32, v4
	v_mul_lo_u32 v0, v1, s53
	s_cselect_b64 s[14:15], -1, 0
	v_add_u32_e32 v157, v168, v0
	s_cmp_eq_u32 s28, 3
	v_mad_u32_u24 v182, v181, s53, v168
	s_setprio 1
	ds_read_b128 v[4:7], v157
	ds_read_b128 v[0:3], v157 offset:4608
	ds_read_b128 v[112:115], v157 offset:32
	ds_read_b128 v[8:11], v182 offset:18432
	ds_read_b128 v[116:119], v182 offset:18464
	s_waitcnt lgkmcnt(1)
	v_mfma_f32_32x32x16_bf16 v[16:31], v[4:7], v[8:11], 0
	ds_read_b128 v[120:123], v157 offset:4640
	v_mul_f32_e32 v48, 0xbfb8aa3b, v48
	v_exp_f32_e32 v198, v48
	v_mul_f32_e32 v48, 0xbfb8aa3b, v49
	v_mfma_f32_32x32x16_bf16 v[0:15], v[0:3], v[8:11], 0
	v_exp_f32_e32 v199, v48
	v_mul_f32_e32 v48, 0xbfb8aa3b, v50
	v_exp_f32_e32 v200, v48
	s_waitcnt lgkmcnt(1)
	v_mfma_f32_32x32x16_bf16 v[16:31], v[112:115], v[116:119], v[16:31]
	v_mul_f32_e32 v48, 0xbfb8aa3b, v51
	v_exp_f32_e32 v201, v48
	v_mul_f32_e32 v48, 0xbfb8aa3b, v52
	s_waitcnt lgkmcnt(0)
	v_mfma_f32_32x32x16_bf16 v[0:15], v[120:123], v[116:119], v[0:15]
	ds_read_b128 v[116:119], v157 offset:4672
	ds_read_b128 v[120:123], v182 offset:18496
	v_exp_f32_e32 v202, v48
	v_mul_f32_e32 v48, 0xbfb8aa3b, v53
	v_exp_f32_e32 v203, v48
	s_waitcnt lgkmcnt(0)
	v_mfma_f32_32x32x16_bf16 v[0:15], v[116:119], v[120:123], v[0:15]
	ds_read_b128 v[116:119], v157 offset:4704
	ds_read_b128 v[112:115], v157 offset:64
	v_mul_f32_e32 v48, 0xbfb8aa3b, v54
	v_exp_f32_e32 v196, v48
	s_waitcnt lgkmcnt(0)
	v_mfma_f32_32x32x16_bf16 v[16:31], v[112:115], v[120:123], v[16:31]
	ds_read_b128 v[120:123], v182 offset:18528
	v_mul_f32_e32 v48, 0xbfb8aa3b, v55
	v_exp_f32_e32 v197, v48
	s_waitcnt lgkmcnt(0)
	v_mfma_f32_32x32x16_bf16 v[0:15], v[116:119], v[120:123], v[0:15]
	ds_read_b128 v[112:115], v157 offset:96
	v_mul_f32_e32 v48, 0xbfb8aa3b, v56
	v_exp_f32_e32 v194, v48
	s_waitcnt lgkmcnt(0)
	v_mfma_f32_32x32x16_bf16 v[16:31], v[112:115], v[120:123], v[16:31]
	v_mul_f32_e32 v48, 0xbfb8aa3b, v57
	v_exp_f32_e32 v195, v48
	s_setprio 0
	s_barrier
; DI float sigmoidf_(float x) { return 1.f / (1.f + __expf(-x)); }
; template <int BN>
; DI void gemm_main(f32x16 (&acc)[2][BN / 64], const GDesc& cur, const GDesc& nxt, GRegs<BN>& R, bool preloaded, char* smem) {
;     ...
;   for (int k0 = 0; k0 < K; k0 += 128) {
;     __syncthreads();
;     GM_STORE(R.ra0, R.rb0)
;     __syncthreads();
;     if (k0 + 128 < K) GM_LOAD(R.ra0, R.rb0, ap, wp, lda, ldw, k0 + 128)
;     else if (nxt.valid) GM_LOAD(R.ra0, R.rb0, apn, wpn, nxt.lda, nxt.ldw, 0)
;     GM_COMPUTE()
;     __syncthreads();
;     GM_STORE(R.ra1, R.rb1)
;     __syncthreads();
;     if (k0 + 192 < K) GM_LOAD(R.ra1, R.rb1, ap, wp, lda, ldw, k0 + 192)
;     else if (nxt.valid) GM_LOAD(R.ra1, R.rb1, apn, wpn, nxt.lda, nxt.ldw, 64)
;     GM_COMPUTE()
; DI void phase_merge(const Params& P, int layer, char* smem) {
;     ...
;         for (int i = 0; i < 16; ++i) G[mi][0][i] = sigmoidf_(G[mi][0][i]);
	s_waitcnt vmcnt(7)
	ds_write_b128 v156, v[76:79]
	ds_write_b128 v156, v[80:83] offset:4608
	ds_write_b128 v156, v[68:71] offset:9216
	ds_write_b128 v156, v[64:67] offset:13824
	ds_write_b128 v156, v[72:75] offset:18432
	s_waitcnt vmcnt(6)
	ds_write_b128 v156, v[84:87] offset:23040
	s_waitcnt lgkmcnt(0)
	s_barrier
	s_setprio 1
	ds_read_b128 v[68:71], v157 offset:4608
	ds_read_b128 v[76:79], v157
	ds_read_b128 v[84:87], v157 offset:32
	ds_read_b128 v[184:187], v182 offset:18432
	ds_read_b128 v[188:191], v182 offset:18464
	s_waitcnt lgkmcnt(1)
	v_mfma_f32_32x32x16_bf16 v[16:31], v[76:79], v[184:187], v[16:31]
	ds_read_b128 v[76:79], v157 offset:4672
	global_load_dwordx4 v[64:67], v[166:167], off offset:384
	v_mul_f32_e32 v48, 0xbfb8aa3b, v58
	v_exp_f32_e32 v192, v48
	v_mfma_f32_32x32x16_bf16 v[0:15], v[68:71], v[184:187], v[0:15]
	ds_read_b128 v[68:71], v157 offset:4640
	global_load_dwordx4 v[80:83], v[174:175], off offset:384
	v_mul_f32_e32 v48, 0xbfb8aa3b, v59
	v_exp_f32_e32 v193, v48
	s_waitcnt lgkmcnt(2)
	v_mfma_f32_32x32x16_bf16 v[16:31], v[84:87], v[188:191], v[16:31]
	ds_read_b128 v[84:87], v182 offset:18496
	global_load_dwordx4 v[72:75], v[164:165], off offset:384
	v_mul_f32_e32 v48, 0xbfb8aa3b, v60
	v_exp_f32_e32 v54, v48
	s_waitcnt lgkmcnt(1)
	v_mfma_f32_32x32x16_bf16 v[0:15], v[68:71], v[188:191], v[0:15]
	ds_read_b128 v[68:71], v157 offset:64
	global_load_dwordx4 v[120:123], v[162:163], off offset:384
	v_mul_f32_e32 v48, 0xbfb8aa3b, v61
	v_mul_f32_e32 v32, 0xbfb8aa3b, v32
	s_waitcnt lgkmcnt(0)
	v_mfma_f32_32x32x16_bf16 v[16:31], v[68:71], v[84:87], v[16:31]
	global_load_dwordx4 v[116:119], v[176:177], off offset:384
	v_exp_f32_e32 v55, v48
	v_mul_f32_e32 v48, 0xbfb8aa3b, v62
	v_mfma_f32_32x32x16_bf16 v[0:15], v[76:79], v[84:87], v[0:15]
	ds_read_b128 v[84:87], v182 offset:18528
	ds_read_b128 v[76:79], v157 offset:4704
	global_load_dwordx4 v[112:115], v[178:179], off offset:384
	v_exp_f32_e32 v62, v32
	v_mul_f32_e32 v32, 0xbfb8aa3b, v33
	s_waitcnt lgkmcnt(0)
	v_mfma_f32_32x32x16_bf16 v[0:15], v[76:79], v[84:87], v[0:15]
	ds_read_b128 v[68:71], v157 offset:96
	v_exp_f32_e32 v58, v48
	v_mul_f32_e32 v48, 0xbfb8aa3b, v63
	s_waitcnt lgkmcnt(0)
	v_mfma_f32_32x32x16_bf16 v[16:31], v[68:71], v[84:87], v[16:31]
	v_exp_f32_e32 v63, v32
	v_mul_f32_e32 v32, 0xbfb8aa3b, v34
	s_setprio 0
	s_barrier
	s_waitcnt vmcnt(8)
	ds_write_b128 v156, v[100:103]
	s_waitcnt vmcnt(7)
	ds_write_b128 v156, v[108:111] offset:4608
	ds_write_b128 v156, v[92:95] offset:9216
	ds_write_b128 v156, v[88:91] offset:13824
	ds_write_b128 v156, v[96:99] offset:18432
	s_waitcnt vmcnt(6)
	ds_write_b128 v156, v[104:107] offset:23040
	s_waitcnt lgkmcnt(0)
	s_barrier
	s_setprio 1
	ds_read_b128 v[100:103], v157 offset:4608
	ds_read_b128 v[104:107], v157
	ds_read_b128 v[108:111], v157 offset:32
	ds_read_b128 v[184:187], v182 offset:18432
	ds_read_b128 v[188:191], v182 offset:18464
	s_waitcnt lgkmcnt(1)
	v_mfma_f32_32x32x16_bf16 v[16:31], v[104:107], v[184:187], v[16:31]
	ds_read_b128 v[104:107], v157 offset:4672
	global_load_dwordx4 v[68:71], v[166:167], off offset:512
	v_exp_f32_e32 v60, v32
	v_mul_f32_e32 v32, 0xbfb8aa3b, v35
	v_mfma_f32_32x32x16_bf16 v[0:15], v[100:103], v[184:187], v[0:15]
	ds_read_b128 v[100:103], v157 offset:4640
	global_load_dwordx4 v[84:87], v[174:175], off offset:512
	v_exp_f32_e32 v61, v32
	v_mul_f32_e32 v32, 0xbfb8aa3b, v36
	s_waitcnt lgkmcnt(2)
	v_mfma_f32_32x32x16_bf16 v[16:31], v[108:111], v[188:191], v[16:31]
	ds_read_b128 v[108:111], v182 offset:18496
	global_load_dwordx4 v[76:79], v[164:165], off offset:512
	v_exp_f32_e32 v56, v32
	v_mul_f32_e32 v32, 0xbfb8aa3b, v37
	s_waitcnt lgkmcnt(1)
	v_mfma_f32_32x32x16_bf16 v[0:15], v[100:103], v[188:191], v[0:15]
	ds_read_b128 v[100:103], v157 offset:64
	global_load_dwordx4 v[96:99], v[162:163], off offset:512
	v_exp_f32_e32 v57, v32
	v_mul_f32_e32 v32, 0xbfb8aa3b, v38
	s_waitcnt lgkmcnt(0)
	v_mfma_f32_32x32x16_bf16 v[16:31], v[100:103], v[108:111], v[16:31]
	global_load_dwordx4 v[92:95], v[176:177], off offset:512
	v_exp_f32_e32 v52, v32
	v_mul_f32_e32 v32, 0xbfb8aa3b, v39
	v_mfma_f32_32x32x16_bf16 v[0:15], v[104:107], v[108:111], v[0:15]
	ds_read_b128 v[108:111], v182 offset:18528
	ds_read_b128 v[104:107], v157 offset:4704
	global_load_dwordx4 v[88:91], v[178:179], off offset:512
	v_exp_f32_e32 v53, v32
	v_mul_f32_e32 v32, 0xbfb8aa3b, v40
	s_waitcnt lgkmcnt(0)
	v_mfma_f32_32x32x16_bf16 v[0:15], v[104:107], v[108:111], v[0:15]
	ds_read_b128 v[100:103], v157 offset:96
	v_exp_f32_e32 v50, v32
	v_mul_f32_e32 v32, 0xbfb8aa3b, v41
	s_waitcnt lgkmcnt(0)
	v_mfma_f32_32x32x16_bf16 v[16:31], v[100:103], v[108:111], v[16:31]
	v_exp_f32_e32 v51, v32
	v_mul_f32_e32 v32, 0xbfb8aa3b, v42
	s_setprio 0
	s_barrier
	s_waitcnt vmcnt(8)
	ds_write_b128 v156, v[120:123]
	s_waitcnt vmcnt(7)
	ds_write_b128 v156, v[116:119] offset:4608
	ds_write_b128 v156, v[80:83] offset:9216
	ds_write_b128 v156, v[64:67] offset:13824
	ds_write_b128 v156, v[72:75] offset:18432
	s_waitcnt vmcnt(6)
	ds_write_b128 v156, v[112:115] offset:23040
	s_waitcnt lgkmcnt(0)
	s_barrier
; DI float sigmoidf_(float x) { return 1.f / (1.f + __expf(-x)); }
; template <int BN>
; DI void gemm_main(f32x16 (&acc)[2][BN / 64], const GDesc& cur, const GDesc& nxt, GRegs<BN>& R, bool preloaded, char* smem) {
;     ...
;   for (int k0 = 0; k0 < K; k0 += 128) {
;     __syncthreads();
;     GM_STORE(R.ra0, R.rb0)
;     __syncthreads();
;     if (k0 + 128 < K) GM_LOAD(R.ra0, R.rb0, ap, wp, lda, ldw, k0 + 128)
;     else if (nxt.valid) GM_LOAD(R.ra0, R.rb0, apn, wpn, nxt.lda, nxt.ldw, 0)
;     GM_COMPUTE()
;     __syncthreads();
;     GM_STORE(R.ra1, R.rb1)
;     __syncthreads();
;     if (k0 + 192 < K) GM_LOAD(R.ra1, R.rb1, ap, wp, lda, ldw, k0 + 192)
;     else if (nxt.valid) GM_LOAD(R.ra1, R.rb1, apn, wpn, nxt.lda, nxt.ldw, 64)
;     GM_COMPUTE()
; DI void phase_merge(const Params& P, int layer, char* smem) {
;     ...
;         for (int i = 0; i < 16; ++i) G[mi][0][i] = sigmoidf_(G[mi][0][i]);
	s_setprio 1
	ds_read_b128 v[100:103], v157 offset:4608
	ds_read_b128 v[104:107], v157
	ds_read_b128 v[108:111], v157 offset:32
	ds_read_b128 v[184:187], v182 offset:18432
	ds_read_b128 v[188:191], v182 offset:18464
	s_waitcnt lgkmcnt(1)
	v_mfma_f32_32x32x16_bf16 v[16:31], v[104:107], v[184:187], v[16:31]
	ds_read_b128 v[104:107], v157 offset:4672
	global_load_dwordx4 v[64:67], v[166:167], off offset:640
	v_exp_f32_e32 v59, v48
	v_exp_f32_e32 v48, v32
	v_mfma_f32_32x32x16_bf16 v[0:15], v[100:103], v[184:187], v[0:15]
	ds_read_b128 v[100:103], v157 offset:4640
	global_load_dwordx4 v[80:83], v[174:175], off offset:640
	v_mul_f32_e32 v32, 0xbfb8aa3b, v43
	v_exp_f32_e32 v49, v32
	s_waitcnt lgkmcnt(2)
	v_mfma_f32_32x32x16_bf16 v[16:31], v[108:111], v[188:191], v[16:31]
	ds_read_b128 v[108:111], v182 offset:18496
	global_load_dwordx4 v[72:75], v[164:165], off offset:640
	v_mul_f32_e32 v32, 0xbfb8aa3b, v44
	v_exp_f32_e32 v40, v32
	s_waitcnt lgkmcnt(1)
	v_mfma_f32_32x32x16_bf16 v[0:15], v[100:103], v[188:191], v[0:15]
	ds_read_b128 v[100:103], v157 offset:64
	global_load_dwordx4 v[120:123], v[162:163], off offset:640
	v_mul_f32_e32 v32, 0xbfb8aa3b, v45
	v_exp_f32_e32 v41, v32
	s_waitcnt lgkmcnt(0)
	v_mfma_f32_32x32x16_bf16 v[16:31], v[100:103], v[108:111], v[16:31]
	global_load_dwordx4 v[116:119], v[176:177], off offset:640
	v_mul_f32_e32 v32, 0xbfb8aa3b, v46
	v_exp_f32_e32 v36, v32
	v_mfma_f32_32x32x16_bf16 v[0:15], v[104:107], v[108:111], v[0:15]
	ds_read_b128 v[108:111], v182 offset:18528
	ds_read_b128 v[104:107], v157 offset:4704
	global_load_dwordx4 v[112:115], v[178:179], off offset:640
	v_mul_f32_e32 v32, 0xbfb8aa3b, v47
	v_exp_f32_e32 v37, v32
	s_waitcnt lgkmcnt(0)
	v_mfma_f32_32x32x16_bf16 v[0:15], v[104:107], v[108:111], v[0:15]
	ds_read_b128 v[100:103], v157 offset:96
	v_pk_add_f32 v[32:33], v[198:199], 1.0 op_sel_hi:[1,0]
	v_pk_add_f32 v[54:55], v[54:55], 1.0 op_sel_hi:[1,0]
	s_waitcnt lgkmcnt(0)
	v_mfma_f32_32x32x16_bf16 v[16:31], v[100:103], v[108:111], v[16:31]
	v_pk_add_f32 v[58:59], v[58:59], 1.0 op_sel_hi:[1,0]
	v_pk_add_f32 v[62:63], v[62:63], 1.0 op_sel_hi:[1,0]
	s_setprio 0
	s_barrier
	s_waitcnt vmcnt(8)
	ds_write_b128 v156, v[96:99]
	s_waitcnt vmcnt(7)
	ds_write_b128 v156, v[92:95] offset:4608
	ds_write_b128 v156, v[84:87] offset:9216
	ds_write_b128 v156, v[68:71] offset:13824
	ds_write_b128 v156, v[76:79] offset:18432
	s_waitcnt vmcnt(6)
	ds_write_b128 v156, v[88:91] offset:23040
	s_waitcnt lgkmcnt(0)
	s_barrier
	s_setprio 1
	ds_read_b128 v[68:71], v157 offset:4608
	ds_read_b128 v[76:79], v157
	ds_read_b128 v[84:87], v157 offset:32
	ds_read_b128 v[184:187], v182 offset:18432
	ds_read_b128 v[188:191], v182 offset:18464
	s_waitcnt lgkmcnt(1)
	v_mfma_f32_32x32x16_bf16 v[16:31], v[76:79], v[184:187], v[16:31]
	ds_read_b128 v[76:79], v157 offset:4672
	global_load_dwordx4 v[88:91], v[166:167], off offset:768
	v_pk_add_f32 v[60:61], v[60:61], 1.0 op_sel_hi:[1,0]
	v_rcp_f32_e32 v33, v33
	v_mfma_f32_32x32x16_bf16 v[0:15], v[68:71], v[184:187], v[0:15]
	ds_read_b128 v[68:71], v157 offset:4640
	global_load_dwordx4 v[92:95], v[174:175], off offset:768
	v_pk_add_f32 v[56:57], v[56:57], 1.0 op_sel_hi:[1,0]
	v_pk_add_f32 v[52:53], v[52:53], 1.0 op_sel_hi:[1,0]
	s_waitcnt lgkmcnt(2)
	v_mfma_f32_32x32x16_bf16 v[16:31], v[84:87], v[188:191], v[16:31]
	ds_read_b128 v[84:87], v182 offset:18496
	global_load_dwordx4 v[96:99], v[164:165], off offset:768
	v_pk_add_f32 v[50:51], v[50:51], 1.0 op_sel_hi:[1,0]
	v_rcp_f32_e32 v32, v32
	s_waitcnt lgkmcnt(1)
	v_mfma_f32_32x32x16_bf16 v[0:15], v[68:71], v[188:191], v[0:15]
	ds_read_b128 v[68:71], v157 offset:64
	global_load_dwordx4 v[100:103], v[162:163], off offset:768
	v_pk_add_f32 v[34:35], v[200:201], 1.0 op_sel_hi:[1,0]
	v_pk_add_f32 v[48:49], v[48:49], 1.0 op_sel_hi:[1,0]
	s_waitcnt lgkmcnt(0)
	v_mfma_f32_32x32x16_bf16 v[16:31], v[68:71], v[84:87], v[16:31]
	global_load_dwordx4 v[104:107], v[176:177], off offset:768
	v_pk_add_f32 v[40:41], v[40:41], 1.0 op_sel_hi:[1,0]
	v_pk_add_f32 v[36:37], v[36:37], 1.0 op_sel_hi:[1,0]
	v_mfma_f32_32x32x16_bf16 v[0:15], v[76:79], v[84:87], v[0:15]
	ds_read_b128 v[84:87], v182 offset:18528
	ds_read_b128 v[76:79], v157 offset:4704
	global_load_dwordx4 v[108:111], v[178:179], off offset:768
	v_rcp_f32_e32 v35, v35
	v_rcp_f32_e32 v34, v34
	s_waitcnt lgkmcnt(0)
	v_mfma_f32_32x32x16_bf16 v[0:15], v[76:79], v[84:87], v[0:15]
	ds_read_b128 v[68:71], v157 offset:96
	v_pk_add_f32 v[38:39], v[202:203], 1.0 op_sel_hi:[1,0]
	s_nop 0
	s_waitcnt lgkmcnt(0)
	v_mfma_f32_32x32x16_bf16 v[16:31], v[68:71], v[84:87], v[16:31]
	v_rcp_f32_e32 v39, v39
	v_rcp_f32_e32 v38, v38
	s_setprio 0
	s_barrier
	s_waitcnt vmcnt(8)
	ds_write_b128 v156, v[120:123]
	s_waitcnt vmcnt(7)
	ds_write_b128 v156, v[116:119] offset:4608
	ds_write_b128 v156, v[80:83] offset:9216
	ds_write_b128 v156, v[64:67] offset:13824
	ds_write_b128 v156, v[72:75] offset:18432
	s_waitcnt vmcnt(6)
	ds_write_b128 v156, v[112:115] offset:23040
	s_waitcnt lgkmcnt(0)
	s_barrier
; DI float sigmoidf_(float x) { return 1.f / (1.f + __expf(-x)); }
; template <int BN>
; DI void gemm_main(f32x16 (&acc)[2][BN / 64], const GDesc& cur, const GDesc& nxt, GRegs<BN>& R, bool preloaded, char* smem) {
;     ...
;   for (int k0 = 0; k0 < K; k0 += 128) {
;     __syncthreads();
;     GM_STORE(R.ra0, R.rb0)
;     __syncthreads();
;     if (k0 + 128 < K) GM_LOAD(R.ra0, R.rb0, ap, wp, lda, ldw, k0 + 128)
;     else if (nxt.valid) GM_LOAD(R.ra0, R.rb0, apn, wpn, nxt.lda, nxt.ldw, 0)
;     GM_COMPUTE()
;     __syncthreads();
;     GM_STORE(R.ra1, R.rb1)
;     __syncthreads();
;     if (k0 + 192 < K) GM_LOAD(R.ra1, R.rb1, ap, wp, lda, ldw, k0 + 192)
;     else if (nxt.valid) GM_LOAD(R.ra1, R.rb1, apn, wpn, nxt.lda, nxt.ldw, 64)
;     GM_COMPUTE()
; DI void phase_merge(const Params& P, int layer, char* smem) {
;     ...
;         for (int i = 0; i < 16; ++i) G[mi][0][i] = sigmoidf_(G[mi][0][i]);
	global_load_dwordx4 v[64:67], v[166:167], off offset:896
	global_load_dwordx4 v[68:71], v[174:175], off offset:896
	global_load_dwordx4 v[72:75], v[164:165], off offset:896
	global_load_dwordx4 v[76:79], v[162:163], off offset:896
	global_load_dwordx4 v[80:83], v[176:177], off offset:896
	global_load_dwordx4 v[84:87], v[178:179], off offset:896
	s_setprio 1
	ds_read_b128 v[112:115], v157 offset:4608
	ds_read_b128 v[116:119], v157
	ds_read_b128 v[120:123], v157 offset:32
	ds_read_b128 v[162:165], v182 offset:18432
	ds_read_b128 v[174:177], v182 offset:18464
	s_waitcnt lgkmcnt(1)
	v_mfma_f32_32x32x16_bf16 v[16:31], v[116:119], v[162:165], v[16:31]
	ds_read_b128 v[116:119], v157 offset:4672
	v_pk_add_f32 v[42:43], v[196:197], 1.0 op_sel_hi:[1,0]
	s_nop 0
	v_mfma_f32_32x32x16_bf16 v[0:15], v[112:115], v[162:165], v[0:15]
	ds_read_b128 v[112:115], v157 offset:4640
	v_rcp_f32_e32 v43, v43
	v_rcp_f32_e32 v42, v42
	s_waitcnt lgkmcnt(2)
	v_mfma_f32_32x32x16_bf16 v[16:31], v[120:123], v[174:177], v[16:31]
	ds_read_b128 v[120:123], v182 offset:18496
	v_pk_add_f32 v[44:45], v[194:195], 1.0 op_sel_hi:[1,0]
	s_nop 0
	s_waitcnt lgkmcnt(1)
	v_mfma_f32_32x32x16_bf16 v[0:15], v[112:115], v[174:177], v[0:15]
	ds_read_b128 v[112:115], v157 offset:64
	v_rcp_f32_e32 v45, v45
	v_rcp_f32_e32 v44, v44
	s_waitcnt lgkmcnt(0)
	v_mfma_f32_32x32x16_bf16 v[16:31], v[112:115], v[120:123], v[16:31]
	v_pk_add_f32 v[46:47], v[192:193], 1.0 op_sel_hi:[1,0]
	s_nop 0
	v_mfma_f32_32x32x16_bf16 v[0:15], v[116:119], v[120:123], v[0:15]
	ds_read_b128 v[120:123], v182 offset:18528
	ds_read_b128 v[116:119], v157 offset:4704
	v_rcp_f32_e32 v47, v47
	v_rcp_f32_e32 v46, v46
	s_waitcnt lgkmcnt(0)
	v_mfma_f32_32x32x16_bf16 v[0:15], v[116:119], v[120:123], v[0:15]
	ds_read_b128 v[112:115], v157 offset:96
	v_rcp_f32_e32 v55, v55
	v_rcp_f32_e32 v54, v54
	s_waitcnt lgkmcnt(0)
	v_mfma_f32_32x32x16_bf16 v[16:31], v[112:115], v[120:123], v[16:31]
	v_rcp_f32_e32 v59, v59
	v_rcp_f32_e32 v58, v58
	s_setprio 0
	s_barrier
	s_waitcnt vmcnt(8)
	ds_write_b128 v156, v[100:103]
	s_waitcnt vmcnt(7)
	ds_write_b128 v156, v[104:107] offset:4608
	ds_write_b128 v156, v[92:95] offset:9216
	ds_write_b128 v156, v[88:91] offset:13824
	ds_write_b128 v156, v[96:99] offset:18432
	s_waitcnt vmcnt(6)
	ds_write_b128 v156, v[108:111] offset:23040
	s_waitcnt lgkmcnt(0)
	s_barrier
	s_cbranch_scc1 .LBB0_103
	v_add_co_u32_e32 v88, vcc, 0x30000, v160
	s_nop 1
	v_addc_co_u32_e32 v89, vcc, 0, v161, vcc
	v_add_co_u32_e32 v92, vcc, 0x20000, v160
	s_nop 1
	v_addc_co_u32_e32 v93, vcc, 0, v161, vcc
	v_add_co_u32_e32 v104, vcc, 0x10000, v160
	global_load_dwordx4 v[88:91], v[88:89], off
	s_nop 0
	global_load_dwordx4 v[92:95], v[92:93], off
	v_addc_co_u32_e32 v105, vcc, 0, v161, vcc
	v_add_co_u32_e32 v108, vcc, 0x10000, v158
	global_load_dwordx4 v[96:99], v[158:159], off
	global_load_dwordx4 v[100:103], v[160:161], off
	v_addc_co_u32_e32 v109, vcc, 0, v159, vcc
	global_load_dwordx4 v[104:107], v[104:105], off
	s_nop 0
	global_load_dwordx4 v[108:111], v[108:109], off
.LBB0_103:
	v_mul_u32_u24_e32 v116, 0x90, v181
	s_setprio 1
	ds_read_b128 v[112:115], v157 offset:4608
	ds_read_b128 v[120:123], v157
	v_add_u32_e32 v118, v116, v168
	ds_read_b128 v[162:165], v157 offset:32
	ds_read_b128 v[174:177], v118 offset:18432
	ds_read_b128 v[182:185], v118 offset:18464
	s_waitcnt lgkmcnt(1)
	v_mfma_f32_32x32x16_bf16 v[16:31], v[120:123], v[174:177], v[16:31]
	ds_read_b128 v[120:123], v157 offset:4672
	v_rcp_f32_e32 v63, v63
	v_rcp_f32_e32 v62, v62
	v_mfma_f32_32x32x16_bf16 v[0:15], v[112:115], v[174:177], v[0:15]
	ds_read_b128 v[112:115], v157 offset:4640
	v_rcp_f32_e32 v61, v61
	v_rcp_f32_e32 v60, v60
	s_waitcnt lgkmcnt(2)
	v_mfma_f32_32x32x16_bf16 v[16:31], v[162:165], v[182:185], v[16:31]
	ds_read_b128 v[162:165], v118 offset:18496
	v_rcp_f32_e32 v57, v57
	v_rcp_f32_e32 v56, v56
	s_waitcnt lgkmcnt(1)
	v_mfma_f32_32x32x16_bf16 v[0:15], v[112:115], v[182:185], v[0:15]
	ds_read_b128 v[112:115], v157 offset:64
	v_rcp_f32_e32 v53, v53
	v_rcp_f32_e32 v52, v52
	s_waitcnt lgkmcnt(0)
	v_mfma_f32_32x32x16_bf16 v[16:31], v[112:115], v[162:165], v[16:31]
	v_rcp_f32_e32 v51, v51
	v_rcp_f32_e32 v50, v50
	v_mfma_f32_32x32x16_bf16 v[0:15], v[120:123], v[162:165], v[0:15]
	ds_read_b128 v[162:165], v118 offset:18528
	ds_read_b128 v[120:123], v157 offset:4704
	v_rcp_f32_e32 v49, v49
	v_rcp_f32_e32 v48, v48
	s_waitcnt lgkmcnt(0)
	v_mfma_f32_32x32x16_bf16 v[0:15], v[120:123], v[162:165], v[0:15]
	ds_read_b128 v[112:115], v157 offset:96
	v_rcp_f32_e32 v41, v41
	v_rcp_f32_e32 v40, v40
	s_waitcnt lgkmcnt(0)
	v_mfma_f32_32x32x16_bf16 v[16:31], v[112:115], v[162:165], v[16:31]
	v_rcp_f32_e32 v37, v37
	v_rcp_f32_e32 v36, v36
	s_setprio 0
	s_andn2_b64 vcc, exec, s[14:15]
	s_barrier
	s_waitcnt vmcnt(2)
	ds_write_b128 v156, v[76:79]
	s_waitcnt vmcnt(1)
	ds_write_b128 v156, v[80:83] offset:4608
	ds_write_b128 v156, v[68:71] offset:9216
	ds_write_b128 v156, v[64:67] offset:13824
	ds_write_b128 v156, v[72:75] offset:18432
	s_waitcnt vmcnt(0)
	ds_write_b128 v156, v[84:87] offset:23040
	s_waitcnt lgkmcnt(0)
	s_barrier
	s_cbranch_vccnz .LBB0_105
	v_add_co_u32_e32 v64, vcc, 0x30000, v160
	s_nop 1
	v_addc_co_u32_e32 v65, vcc, 0, v161, vcc
	v_add_co_u32_e32 v68, vcc, 0x20000, v160
	s_nop 1
	v_addc_co_u32_e32 v69, vcc, 0, v161, vcc
	v_add_co_u32_e32 v80, vcc, 0x10000, v160
	global_load_dwordx4 v[64:67], v[64:65], off offset:128
	s_nop 0
	global_load_dwordx4 v[68:71], v[68:69], off offset:128
	v_addc_co_u32_e32 v81, vcc, 0, v161, vcc
	v_add_co_u32_e32 v84, vcc, 0x10000, v158
	global_load_dwordx4 v[72:75], v[158:159], off offset:128
	global_load_dwordx4 v[76:79], v[160:161], off offset:128
	v_addc_co_u32_e32 v85, vcc, 0, v159, vcc
	global_load_dwordx4 v[80:83], v[80:81], off offset:128
	s_nop 0
	global_load_dwordx4 v[84:87], v[84:85], off offset:128
; DI float sigmoidf_(float x) { return 1.f / (1.f + __expf(-x)); }
; DI void phase_merge(const Params& P, int layer, char* smem) {
;     ...
;       gemm_main<64>(G, dG, dP, R, k > 0, smem);
; #pragma unroll
;       for (int mi = 0; mi < 2; ++mi)
; #pragma unroll
;         for (int i = 0; i < 16; ++i) G[mi][0][i] = sigmoidf_(G[mi][0][i]);
;       f32x16 Pk[2][1];
;       zero_acc<1>(Pk);
;       gemm_main<64>(Pk, dP, dN, R, true, smem);
; #pragma unroll
;       for (int mi = 0; mi < 2; ++mi)
; #pragma unroll
;         for (int i = 0; i < 16; ++i) M[mi][0][i] += Pk[mi][0][i] * G[mi][0][i];
;     }
;     int col = n0 + wn * 32 + r;
; #pragma unroll
;     for (int mi = 0; mi < 2; ++mi)
; #pragma unroll
;       for (int g = 0; g < 4; ++g) {
;         int rl = wm * 64 + mi * 32 + 8 * g + 4 * h;
;         st_rm(MG, 1024, m0 + rl, col, M[mi][0][4 * g], M[mi][0][4 * g + 1], M[mi][0][4 * g + 2], M[mi][0][4 * g + 3]);
;       }
.LBB0_105:
	s_setprio 1
	ds_read_b128 v[112:115], v157 offset:4608
	ds_read_b128 v[120:123], v157
	ds_read_b128 v[158:161], v157 offset:32
	ds_read_b128 v[162:165], v118 offset:18432
	ds_read_b128 v[174:177], v118 offset:18464
	s_waitcnt lgkmcnt(1)
	v_mfma_f32_32x32x16_bf16 v[16:31], v[120:123], v[162:165], v[16:31]
	ds_read_b128 v[120:123], v157 offset:4672
	v_mfma_f32_32x32x16_bf16 v[0:15], v[112:115], v[162:165], v[0:15]
	ds_read_b128 v[112:115], v157 offset:4640
	s_waitcnt lgkmcnt(2)
	v_mfma_f32_32x32x16_bf16 v[16:31], v[158:161], v[174:177], v[16:31]
	ds_read_b128 v[158:161], v118 offset:18496
	ds_read_b128 v[116:119], v118 offset:18528
	s_waitcnt lgkmcnt(2)
	v_mfma_f32_32x32x16_bf16 v[0:15], v[112:115], v[174:177], v[0:15]
	s_waitcnt lgkmcnt(1)
	v_mfma_f32_32x32x16_bf16 v[0:15], v[120:123], v[158:161], v[0:15]
	ds_read_b128 v[120:123], v157 offset:4704
	s_waitcnt lgkmcnt(0)
	v_mfma_f32_32x32x16_bf16 v[0:15], v[120:123], v[116:119], v[0:15]
	ds_read_b128 v[112:115], v157 offset:64
	s_waitcnt lgkmcnt(0)
	v_mfma_f32_32x32x16_bf16 v[16:31], v[112:115], v[158:161], v[16:31]
	ds_read_b128 v[112:115], v157 offset:96
	s_waitcnt lgkmcnt(0)
	v_mfma_f32_32x32x16_bf16 v[16:31], v[112:115], v[116:119], v[16:31]
	s_setprio 0
	s_add_u32 s12, s12, 0x200000
	s_addc_u32 s13, s13, 0
	s_add_u32 s10, s10, 0x200000
	s_addc_u32 s11, s11, 0
	s_add_u32 s8, s8, 0x200000
	s_addc_u32 s9, s9, 0
	s_add_u32 s6, s6, 0x200000
	s_addc_u32 s7, s7, 0
	s_nop 2
	v_pk_fma_f32 v[154:155], v[32:33], v[16:17], v[154:155]
	v_pk_fma_f32 v[152:153], v[34:35], v[18:19], v[152:153]
	v_pk_fma_f32 v[150:151], v[38:39], v[20:21], v[150:151]
	v_pk_fma_f32 v[148:149], v[42:43], v[22:23], v[148:149]
	v_pk_fma_f32 v[146:147], v[44:45], v[24:25], v[146:147]
	v_pk_fma_f32 v[144:145], v[46:47], v[26:27], v[144:145]
	v_pk_fma_f32 v[142:143], v[54:55], v[28:29], v[142:143]
	v_pk_fma_f32 v[140:141], v[58:59], v[30:31], v[140:141]
	v_pk_fma_f32 v[138:139], v[62:63], v[0:1], v[138:139]
	v_pk_fma_f32 v[136:137], v[60:61], v[2:3], v[136:137]
	v_pk_fma_f32 v[134:135], v[56:57], v[4:5], v[134:135]
	v_pk_fma_f32 v[132:133], v[52:53], v[6:7], v[132:133]
	v_pk_fma_f32 v[130:131], v[50:51], v[8:9], v[130:131]
	v_pk_fma_f32 v[128:129], v[48:49], v[10:11], v[128:129]
	v_pk_fma_f32 v[126:127], v[40:41], v[12:13], v[126:127]
	s_cmp_eq_u32 s4, 4
	v_pk_fma_f32 v[124:125], v[36:37], v[14:15], v[124:125]
	s_cbranch_scc0 .LBB0_88
	v_or_b32_e32 v0, s26, v173
	v_add_u32_e32 v2, s25, v180
	v_readlane_b32 s6, v251, 10
	v_ashrrev_i32_e32 v1, 31, v0
	v_readlane_b32 s7, v251, 11
	v_ashrrev_i32_e32 v3, 31, v2
	v_lshlrev_b64 v[4:5], 11, v[2:3]
	v_lshl_add_u64 v[0:1], v[0:1], 1, s[6:7]
	v_lshl_add_u64 v[4:5], v[0:1], 0, v[4:5]
	v_cvt_pk_bf16_f32 v3, v154, s0
	global_store_short v[4:5], v3, off
	v_cvt_pk_bf16_f32 v3, v155, s0
	s_movk_i32 s4, 0x1000
	global_store_short v[4:5], v3, off offset:2048
	v_add_co_u32_e32 v4, vcc, s4, v4
	v_cvt_pk_bf16_f32 v3, v152, s0
	s_nop 0
	v_addc_co_u32_e32 v5, vcc, 0, v5, vcc
	global_store_short v[4:5], v3, off
	v_cvt_pk_bf16_f32 v3, v153, s0
	global_store_short v[4:5], v3, off offset:2048
	v_or_b32_e32 v4, 8, v2
	v_ashrrev_i32_e32 v5, 31, v4
	v_lshlrev_b64 v[4:5], 11, v[4:5]
	v_lshl_add_u64 v[4:5], v[0:1], 0, v[4:5]
	v_cvt_pk_bf16_f32 v3, v150, s0
	global_store_short v[4:5], v3, off
	v_cvt_pk_bf16_f32 v3, v151, s0
	global_store_short v[4:5], v3, off offset:2048
	v_add_co_u32_e32 v4, vcc, s4, v4
	v_cvt_pk_bf16_f32 v3, v148, s0
	s_nop 0
	v_addc_co_u32_e32 v5, vcc, 0, v5, vcc
	global_store_short v[4:5], v3, off
	v_cvt_pk_bf16_f32 v3, v149, s0
	global_store_short v[4:5], v3, off offset:2048
	v_or_b32_e32 v4, 16, v2
	v_ashrrev_i32_e32 v5, 31, v4
	v_lshlrev_b64 v[4:5], 11, v[4:5]
	v_lshl_add_u64 v[4:5], v[0:1], 0, v[4:5]
	v_cvt_pk_bf16_f32 v3, v146, s0
	global_store_short v[4:5], v3, off
	v_cvt_pk_bf16_f32 v3, v147, s0
	global_store_short v[4:5], v3, off offset:2048
	v_add_co_u32_e32 v4, vcc, s4, v4
	v_cvt_pk_bf16_f32 v3, v144, s0
	s_nop 0
	v_addc_co_u32_e32 v5, vcc, 0, v5, vcc
	global_store_short v[4:5], v3, off
	v_cvt_pk_bf16_f32 v3, v145, s0
	global_store_short v[4:5], v3, off offset:2048
	v_or_b32_e32 v4, 24, v2
	v_ashrrev_i32_e32 v5, 31, v4
	v_lshlrev_b64 v[4:5], 11, v[4:5]
	v_lshl_add_u64 v[4:5], v[0:1], 0, v[4:5]
	v_cvt_pk_bf16_f32 v3, v142, s0
	global_store_short v[4:5], v3, off
	v_cvt_pk_bf16_f32 v3, v143, s0
	global_store_short v[4:5], v3, off offset:2048
	v_add_co_u32_e32 v4, vcc, s4, v4
	v_cvt_pk_bf16_f32 v3, v140, s0
	s_nop 0
	v_addc_co_u32_e32 v5, vcc, 0, v5, vcc
	global_store_short v[4:5], v3, off
	v_cvt_pk_bf16_f32 v3, v141, s0
	global_store_short v[4:5], v3, off offset:2048
	v_or_b32_e32 v4, 32, v2
	v_ashrrev_i32_e32 v5, 31, v4
	v_lshlrev_b64 v[4:5], 11, v[4:5]
	v_lshl_add_u64 v[4:5], v[0:1], 0, v[4:5]
	v_cvt_pk_bf16_f32 v3, v138, s0
	global_store_short v[4:5], v3, off
	v_cvt_pk_bf16_f32 v3, v139, s0
	global_store_short v[4:5], v3, off offset:2048
	v_add_co_u32_e32 v4, vcc, s4, v4
	v_cvt_pk_bf16_f32 v3, v136, s0
	s_nop 0
	v_addc_co_u32_e32 v5, vcc, 0, v5, vcc
	global_store_short v[4:5], v3, off
	v_cvt_pk_bf16_f32 v3, v137, s0
	global_store_short v[4:5], v3, off offset:2048
	v_or_b32_e32 v4, 40, v2
	v_ashrrev_i32_e32 v5, 31, v4
	v_lshlrev_b64 v[4:5], 11, v[4:5]
	v_lshl_add_u64 v[4:5], v[0:1], 0, v[4:5]
	v_cvt_pk_bf16_f32 v3, v134, s0
	global_store_short v[4:5], v3, off
	v_cvt_pk_bf16_f32 v3, v135, s0
	global_store_short v[4:5], v3, off offset:2048
	v_add_co_u32_e32 v4, vcc, s4, v4
	v_cvt_pk_bf16_f32 v3, v132, s0
	s_nop 0
	v_addc_co_u32_e32 v5, vcc, 0, v5, vcc
	global_store_short v[4:5], v3, off
	v_cvt_pk_bf16_f32 v3, v133, s0
	global_store_short v[4:5], v3, off offset:2048
	v_or_b32_e32 v4, 48, v2
	v_ashrrev_i32_e32 v5, 31, v4
	v_lshlrev_b64 v[4:5], 11, v[4:5]
	v_lshl_add_u64 v[4:5], v[0:1], 0, v[4:5]
	v_cvt_pk_bf16_f32 v3, v130, s0
	global_store_short v[4:5], v3, off
	v_cvt_pk_bf16_f32 v3, v131, s0
	global_store_short v[4:5], v3, off offset:2048
	v_add_co_u32_e32 v4, vcc, s4, v4
	v_cvt_pk_bf16_f32 v3, v128, s0
	s_nop 0
	v_addc_co_u32_e32 v5, vcc, 0, v5, vcc
	global_store_short v[4:5], v3, off
	v_cvt_pk_bf16_f32 v3, v129, s0
	v_or_b32_e32 v2, 56, v2
	global_store_short v[4:5], v3, off offset:2048
	v_ashrrev_i32_e32 v3, 31, v2
	v_lshlrev_b64 v[2:3], 11, v[2:3]
	v_lshl_add_u64 v[0:1], v[0:1], 0, v[2:3]
	v_cvt_pk_bf16_f32 v2, v126, s0
	global_store_short v[0:1], v2, off
	v_cvt_pk_bf16_f32 v2, v127, s0
	global_store_short v[0:1], v2, off offset:2048
	v_add_co_u32_e32 v0, vcc, 0x1000, v0
	v_readlane_b32 s6, v253, 53
	v_cvt_pk_bf16_f32 v2, v124, s0
	v_addc_co_u32_e32 v1, vcc, 0, v1, vcc
	s_add_i32 s24, s24, s6
	v_readlane_b32 s4, v254, 49
	global_store_short v[0:1], v2, off
	v_cvt_pk_bf16_f32 v2, v125, s0
	s_cmp_ge_i32 s24, s4
	v_readlane_b32 s7, v253, 54
	global_store_short v[0:1], v2, off offset:2048
	s_cbranch_scc0 .LBB0_85
